# gate/up and out-proj unit headers: dropped the full vmcnt(0) drain (the hand-written epilogues consume all their loads; only stores are outstanding)
# speedup vs baseline: 1.0055x; 1.0055x over previous
; template <class Epi, class Sched, bool ALIGN_EPI>
; DI void gemm_phase(LAS unsigned char* lds, const Gemm g, const Sched& S, const Epi& E) {
;     ...
;         const bool has_next = S.next(ui + 1, nxt);
;         const char* nA = has_next ? (const char*)g.A + S.a_row(nxt.pm) * rowb + (size_t)nxt.kt0 * kstep : cA; const char* nB = has_next ? (const char*)g.Bt + (size_t)nxt.pn * 2 * hstep + (size_t)nxt.kt0 * kstep : cB;
;         const int nt = cur.nkt;
;         for (int t = 0; t < nt; t += 2) {
;             const bool last = (t == nt - 2);
;             const char* a1 = cA + (size_t)(t + 1) * kstep;
;             const char* a2 = last ? nA : cA + (size_t)(t + 2) * kstep; const char* b2 = last ? nB : cB + (size_t)(t + 2) * kstep;
;             const char* a3 = a2 + kstep; const char* b3 = b2 + kstep;
;             PG8_LDB(B0, 0, 0); PG8_LDB(B1, 0, 1); PG8_SCHED; PG8_LDA(At, 0, 0); PG8_STAGE(PG8_SA(1, 1), a1 + hstep, voffA);
;             PG8_WAIT_V(8); PG8_WAIT_L(0); PG8_BAR; PG8_MMA(0, 0, At, B0); PG8_MMA(0, 1, At, B1); PG8_BAR; PG8_SCHED;
;             PG8_LDA(At, 0, 1); PG8_STAGE(PG8_SB(0, 0), b2, voffA); PG8_STAGE(PG8_SB(0, 1), b2 + hstep, voffA); PG8_STAGE(PG8_SA(0, 0), a2, voffA);
;             PG8_WAIT_V(8); PG8_WAIT_L(0); PG8_BAR; PG8_MMA(1, 0, At, B0); PG8_MMA(1, 1, At, B1); PG8_BAR; PG8_SCHED;
;             PG8_LDB(B0, 1, 0); PG8_LDB(B1, 1, 1); PG8_SCHED; PG8_LDA(At, 1, 0); PG8_STAGE(PG8_SA(0, 1), a2 + hstep, voffA);
;             PG8_WAIT_V(8); PG8_WAIT_L(0); PG8_BAR; PG8_MMA(0, 0, At, B0); PG8_MMA(0, 1, At, B1); PG8_BAR; PG8_SCHED;
;             PG8_LDA(At, 1, 1); PG8_STAGE(PG8_SB(1, 0), b3, voffA); PG8_STAGE(PG8_SB(1, 1), b3 + hstep, voffA); PG8_STAGE(PG8_SA(1, 0), a3, voffA);
;             PG8_WAIT_V(8); PG8_WAIT_L(0); PG8_BAR; PG8_MMA(1, 0, At, B0); PG8_MMA(1, 1, At, B1); PG8_BAR; PG8_SCHED;
;         }
;         if constexpr (ALIGN_EPI) { if (wr == 0) PG8_BAR; }
;         E(acc, cur, wr, wc, fr, fq, lds + RING_BYTES);
;         if constexpr (NREP(7) == 2 && Epi::PROBE2) E(acc, cur, wr, wc, fr, fq, lds + RING_BYTES);
;         if (!has_next) break;
; #pragma unroll
;         for (int a = 0; a < 2; ++a)
; #pragma unroll
;             for (int b = 0; b < 2; ++b)
; #pragma unroll
;                 for (int m = 0; m < 4; ++m)
; #pragma unroll
;                     for (int n = 0; n < 2; ++n) acc[a][b][m][n] = (f32x4){0.f, 0.f, 0.f, 0.f};
.LBB0_825:
	s_ashr_i32 s23, s22, 31
	s_lshl_b64 s[26:27], s[22:23], 19
	v_readlane_b32 s23, v253, 12
	s_add_u32 s26, s23, s26
	v_readlane_b32 s23, v253, 13
	s_addc_u32 s27, s23, s27
	s_and_b64 s[34:35], s[34:35], exec
	s_cselect_b32 s23, s27, s31
	s_cselect_b32 s29, s26, s30
	s_add_u32 s0, s0, 0x40080
	s_addc_u32 s1, s1, 0
	s_add_u32 s43, s30, 0x100
	v_mov_b32_e32 v0, 0
	s_addc_u32 s44, s31, 0
	s_mov_b32 s45, -2
	v_mov_b32_e32 v1, v0
	v_mov_b32_e32 v2, v0
	v_mov_b32_e32 v3, v0
	v_mov_b32_e32 v80, v0
	v_mov_b32_e32 v81, v0
	v_mov_b32_e32 v82, v0
	v_mov_b32_e32 v83, v0
	v_mov_b32_e32 v8, v0
	v_mov_b32_e32 v9, v0
	v_mov_b32_e32 v10, v0
	v_mov_b32_e32 v11, v0
	v_mov_b32_e32 v88, v0
	v_mov_b32_e32 v89, v0
	v_mov_b32_e32 v90, v0
	v_mov_b32_e32 v91, v0
	v_mov_b32_e32 v16, v0
	v_mov_b32_e32 v17, v0
	v_mov_b32_e32 v18, v0
	v_mov_b32_e32 v19, v0
	v_mov_b32_e32 v96, v0
	v_mov_b32_e32 v97, v0
	v_mov_b32_e32 v98, v0
	v_mov_b32_e32 v99, v0
	v_mov_b32_e32 v24, v0
	v_mov_b32_e32 v25, v0
	v_mov_b32_e32 v26, v0
	v_mov_b32_e32 v27, v0
	v_mov_b32_e32 v104, v0
	v_mov_b32_e32 v105, v0
	v_mov_b32_e32 v106, v0
	v_mov_b32_e32 v107, v0
	v_mov_b32_e32 v4, v0
	v_mov_b32_e32 v5, v0
	v_mov_b32_e32 v6, v0
	v_mov_b32_e32 v7, v0
	v_mov_b32_e32 v84, v0
	v_mov_b32_e32 v85, v0
	v_mov_b32_e32 v86, v0
	v_mov_b32_e32 v87, v0
	v_mov_b32_e32 v12, v0
	v_mov_b32_e32 v13, v0
	v_mov_b32_e32 v14, v0
	v_mov_b32_e32 v15, v0
	v_mov_b32_e32 v92, v0
	v_mov_b32_e32 v93, v0
	v_mov_b32_e32 v94, v0
	v_mov_b32_e32 v95, v0
	v_mov_b32_e32 v20, v0
	v_mov_b32_e32 v21, v0
	v_mov_b32_e32 v22, v0
	v_mov_b32_e32 v23, v0
	v_mov_b32_e32 v100, v0
	v_mov_b32_e32 v101, v0
	v_mov_b32_e32 v102, v0
	v_mov_b32_e32 v103, v0
	v_mov_b32_e32 v28, v0
	v_mov_b32_e32 v29, v0
	v_mov_b32_e32 v30, v0
	v_mov_b32_e32 v31, v0
	v_mov_b32_e32 v108, v0
	v_mov_b32_e32 v109, v0
	v_mov_b32_e32 v110, v0
	v_mov_b32_e32 v111, v0
	v_mov_b32_e32 v32, v0
	v_mov_b32_e32 v33, v0
	v_mov_b32_e32 v34, v0
	v_mov_b32_e32 v35, v0
	v_mov_b32_e32 v112, v0
	v_mov_b32_e32 v113, v0
	v_mov_b32_e32 v114, v0
	v_mov_b32_e32 v115, v0
	v_mov_b32_e32 v40, v0
	v_mov_b32_e32 v41, v0
	v_mov_b32_e32 v42, v0
	v_mov_b32_e32 v43, v0
	v_mov_b32_e32 v120, v0
	v_mov_b32_e32 v121, v0
	v_mov_b32_e32 v122, v0
	v_mov_b32_e32 v123, v0
	v_mov_b32_e32 v64, v0
	v_mov_b32_e32 v65, v0
	v_mov_b32_e32 v66, v0
	v_mov_b32_e32 v67, v0
	v_mov_b32_e32 v144, v0
	v_mov_b32_e32 v145, v0
	v_mov_b32_e32 v146, v0
	v_mov_b32_e32 v147, v0
	v_mov_b32_e32 v72, v0
	v_mov_b32_e32 v73, v0
	v_mov_b32_e32 v74, v0
	v_mov_b32_e32 v75, v0
	v_mov_b32_e32 v152, v0
	v_mov_b32_e32 v153, v0
	v_mov_b32_e32 v154, v0
	v_mov_b32_e32 v155, v0
	v_mov_b32_e32 v36, v0
	v_mov_b32_e32 v37, v0
	v_mov_b32_e32 v38, v0
	v_mov_b32_e32 v39, v0
	v_mov_b32_e32 v116, v0
	v_mov_b32_e32 v117, v0
	v_mov_b32_e32 v118, v0
	v_mov_b32_e32 v119, v0
	v_mov_b32_e32 v60, v0
	v_mov_b32_e32 v61, v0
	v_mov_b32_e32 v62, v0
	v_mov_b32_e32 v63, v0
	v_mov_b32_e32 v140, v0
	v_mov_b32_e32 v141, v0
	v_mov_b32_e32 v142, v0
	v_mov_b32_e32 v143, v0
	v_mov_b32_e32 v68, v0
	v_mov_b32_e32 v69, v0
	v_mov_b32_e32 v70, v0
	v_mov_b32_e32 v71, v0
	v_mov_b32_e32 v148, v0
	v_mov_b32_e32 v149, v0
	v_mov_b32_e32 v150, v0
	v_mov_b32_e32 v151, v0
	v_mov_b32_e32 v76, v0
	v_mov_b32_e32 v77, v0
	v_mov_b32_e32 v78, v0
	v_mov_b32_e32 v79, v0
	v_mov_b32_e32 v156, v0
	v_mov_b32_e32 v157, v0
	v_mov_b32_e32 v158, v0
	v_mov_b32_e32 v159, v0

;     DI bool next(int i, Unit& u) const {
;         if (i >= cnt) return false;
;         const int idx = s + i * stride;
;         if (KIND == 4) { const int g = idx / 176, w = idx - 176 * g, gsz = (73 - 8 * g) < 8 ? (73 - 8 * g) : 8;
;             u.pm = 8 * g + w % gsz; u.pn = w / gsz; u.kt0 = 0; u.nkt = 16; }
;         else { u.pm = idx >> 2; u.pn = idx & 3; u.kt0 = 0; u.nkt = KIND == 5 ? 44 : 16; }
;         return true;
; template <class Epi, class Sched, bool ALIGN_EPI>
; DI void gemm_phase(LAS unsigned char* lds, const Gemm g, const Sched& S, const Epi& E) {
;     ...
;         const bool has_next = S.next(ui + 1, nxt);
;         const char* nA = has_next ? (const char*)g.A + S.a_row(nxt.pm) * rowb + (size_t)nxt.kt0 * kstep : cA; const char* nB = has_next ? (const char*)g.Bt + (size_t)nxt.pn * 2 * hstep + (size_t)nxt.kt0 * kstep : cB;
;         const int nt = cur.nkt;
;         for (int t = 0; t < nt; t += 2) {
;             const bool last = (t == nt - 2);
;             const char* a1 = cA + (size_t)(t + 1) * kstep;
;             const char* a2 = last ? nA : cA + (size_t)(t + 2) * kstep; const char* b2 = last ? nB : cB + (size_t)(t + 2) * kstep;
;             const char* a3 = a2 + kstep; const char* b3 = b2 + kstep;
;             PG8_LDB(B0, 0, 0); PG8_LDB(B1, 0, 1); PG8_SCHED; PG8_LDA(At, 0, 0); PG8_STAGE(PG8_SA(1, 1), a1 + hstep, voffA);
;             PG8_WAIT_V(8); PG8_WAIT_L(0); PG8_BAR; PG8_MMA(0, 0, At, B0); PG8_MMA(0, 1, At, B1); PG8_BAR; PG8_SCHED;
;             PG8_LDA(At, 0, 1); PG8_STAGE(PG8_SB(0, 0), b2, voffA); PG8_STAGE(PG8_SB(0, 1), b2 + hstep, voffA); PG8_STAGE(PG8_SA(0, 0), a2, voffA);
;             PG8_WAIT_V(8); PG8_WAIT_L(0); PG8_BAR; PG8_MMA(1, 0, At, B0); PG8_MMA(1, 1, At, B1); PG8_BAR; PG8_SCHED;
;             PG8_LDB(B0, 1, 0); PG8_LDB(B1, 1, 1); PG8_SCHED; PG8_LDA(At, 1, 0); PG8_STAGE(PG8_SA(0, 1), a2 + hstep, voffA);
;             PG8_WAIT_V(8); PG8_WAIT_L(0); PG8_BAR; PG8_MMA(0, 0, At, B0); PG8_MMA(0, 1, At, B1); PG8_BAR; PG8_SCHED;
;             PG8_LDA(At, 1, 1); PG8_STAGE(PG8_SB(1, 0), b3, voffA); PG8_STAGE(PG8_SB(1, 1), b3 + hstep, voffA); PG8_STAGE(PG8_SA(1, 0), a3, voffA);
;             PG8_WAIT_V(8); PG8_WAIT_L(0); PG8_BAR; PG8_MMA(1, 0, At, B0); PG8_MMA(1, 1, At, B1); PG8_BAR; PG8_SCHED;
;         }
;         if constexpr (ALIGN_EPI) { if (wr == 0) PG8_BAR; }
;         E(acc, cur, wr, wc, fr, fq, lds + RING_BYTES);
.LBB0_956:
	s_mov_b32 s30, s29
	s_add_i32 s29, s29, 1
	s_cmp_lt_u32 s29, s91
	s_mul_i32 s5, s29, s90
	s_cselect_b64 s[18:19], -1, 0
	s_add_i32 s5, s5, s89
	s_ashr_i32 s5, s5, 2
	s_mov_b64 s[16:17], s[6:7]
	s_and_b64 s[6:7], s[18:19], exec
	s_mov_b32 s31, s4
	s_cselect_b32 s4, s5, s4
	s_mov_b32 s33, s14
	s_cselect_b32 s14, s21, s14
	s_ashr_i32 s5, s4, 31
	s_lshl_b64 s[6:7], s[4:5], 19
	s_mov_b64 s[0:1], s[8:9]
	s_add_u32 s8, s52, s6
	s_addc_u32 s9, s53, s7
	s_and_b64 s[6:7], s[18:19], exec
	s_cselect_b32 s5, s9, s1
	s_cselect_b32 s34, s8, s0
	s_ashr_i32 s15, s14, 31
	s_lshl_b64 s[6:7], s[14:15], 19
	s_add_u32 s6, s60, s6
	s_addc_u32 s7, s82, s7
	s_and_b64 s[18:19], s[18:19], exec
	s_cselect_b32 s15, s7, s17
	s_cselect_b32 s35, s6, s16
	s_add_u32 s0, s0, 0x40080
	s_addc_u32 s1, s1, 0
	s_add_u32 s36, s16, 0x100
	v_mov_b32_e32 v0, 0
	s_addc_u32 s37, s17, 0
	s_mov_b32 s42, -2
	s_waitcnt lgkmcnt(0)
	v_mov_b32_e32 v1, v0
	v_mov_b32_e32 v2, v0
	v_mov_b32_e32 v3, v0
	v_mov_b32_e32 v4, v0
	v_mov_b32_e32 v5, v0
	v_mov_b32_e32 v6, v0
	v_mov_b32_e32 v7, v0
	v_mov_b32_e32 v16, v0
	v_mov_b32_e32 v17, v0
	v_mov_b32_e32 v18, v0
	v_mov_b32_e32 v19, v0
	v_mov_b32_e32 v20, v0
	v_mov_b32_e32 v21, v0
	v_mov_b32_e32 v22, v0
	v_mov_b32_e32 v23, v0
	v_mov_b32_e32 v32, v0
	v_mov_b32_e32 v33, v0
	v_mov_b32_e32 v34, v0
	v_mov_b32_e32 v35, v0
	v_mov_b32_e32 v36, v0
	v_mov_b32_e32 v37, v0
	v_mov_b32_e32 v38, v0
	v_mov_b32_e32 v39, v0
	v_mov_b32_e32 v48, v0
	v_mov_b32_e32 v49, v0
	v_mov_b32_e32 v50, v0
	v_mov_b32_e32 v51, v0
	v_mov_b32_e32 v52, v0
	v_mov_b32_e32 v53, v0
	v_mov_b32_e32 v54, v0
	v_mov_b32_e32 v55, v0
	v_mov_b32_e32 v8, v0
	v_mov_b32_e32 v9, v0
	v_mov_b32_e32 v10, v0
	v_mov_b32_e32 v11, v0
	v_mov_b32_e32 v12, v0
	v_mov_b32_e32 v13, v0
	v_mov_b32_e32 v14, v0
	v_mov_b32_e32 v15, v0
	v_mov_b32_e32 v24, v0
	v_mov_b32_e32 v25, v0
	v_mov_b32_e32 v26, v0
	v_mov_b32_e32 v27, v0
	v_mov_b32_e32 v28, v0
	v_mov_b32_e32 v29, v0
	v_mov_b32_e32 v30, v0
	v_mov_b32_e32 v31, v0
	v_mov_b32_e32 v40, v0
	v_mov_b32_e32 v41, v0
	v_mov_b32_e32 v42, v0
	v_mov_b32_e32 v43, v0
	v_mov_b32_e32 v44, v0
	v_mov_b32_e32 v45, v0
	v_mov_b32_e32 v46, v0
	v_mov_b32_e32 v47, v0
	v_mov_b32_e32 v56, v0
	v_mov_b32_e32 v57, v0
	v_mov_b32_e32 v58, v0
	v_mov_b32_e32 v59, v0
	v_mov_b32_e32 v60, v0
	v_mov_b32_e32 v61, v0
	v_mov_b32_e32 v62, v0
	v_mov_b32_e32 v63, v0
	v_mov_b32_e32 v64, v0
	v_mov_b32_e32 v65, v0
	v_mov_b32_e32 v66, v0
	v_mov_b32_e32 v67, v0
	v_mov_b32_e32 v68, v0
	v_mov_b32_e32 v69, v0
	v_mov_b32_e32 v70, v0
	v_mov_b32_e32 v71, v0
	v_mov_b32_e32 v80, v0
	v_mov_b32_e32 v81, v0
	v_mov_b32_e32 v82, v0
	v_mov_b32_e32 v83, v0
	v_mov_b32_e32 v84, v0
	v_mov_b32_e32 v85, v0
	v_mov_b32_e32 v86, v0
	v_mov_b32_e32 v87, v0
	v_mov_b32_e32 v96, v0
	v_mov_b32_e32 v97, v0
	v_mov_b32_e32 v98, v0
	v_mov_b32_e32 v99, v0
	v_mov_b32_e32 v100, v0
	v_mov_b32_e32 v101, v0
	v_mov_b32_e32 v102, v0
	v_mov_b32_e32 v103, v0
	v_mov_b32_e32 v112, v0
	v_mov_b32_e32 v113, v0
	v_mov_b32_e32 v114, v0
	v_mov_b32_e32 v115, v0
	v_mov_b32_e32 v116, v0
	v_mov_b32_e32 v117, v0
	v_mov_b32_e32 v118, v0
	v_mov_b32_e32 v119, v0
	v_mov_b32_e32 v72, v0
	v_mov_b32_e32 v73, v0
	v_mov_b32_e32 v74, v0
	v_mov_b32_e32 v75, v0
	v_mov_b32_e32 v76, v0
	v_mov_b32_e32 v77, v0
	v_mov_b32_e32 v78, v0
	v_mov_b32_e32 v79, v0
	v_mov_b32_e32 v88, v0
	v_mov_b32_e32 v89, v0
	v_mov_b32_e32 v90, v0
	v_mov_b32_e32 v91, v0
	v_mov_b32_e32 v92, v0
	v_mov_b32_e32 v93, v0
	v_mov_b32_e32 v94, v0
	v_mov_b32_e32 v95, v0
	v_mov_b32_e32 v104, v0
	v_mov_b32_e32 v105, v0
	v_mov_b32_e32 v106, v0
	v_mov_b32_e32 v107, v0
	v_mov_b32_e32 v108, v0
	v_mov_b32_e32 v109, v0
	v_mov_b32_e32 v110, v0
	v_mov_b32_e32 v111, v0
	v_mov_b32_e32 v120, v0
	v_mov_b32_e32 v121, v0
	v_mov_b32_e32 v122, v0
	v_mov_b32_e32 v123, v0
	v_mov_b32_e32 v124, v0
	v_mov_b32_e32 v125, v0
	v_mov_b32_e32 v126, v0
	v_mov_b32_e32 v127, v0
